# on top of v62: HGRN compute waves request the next chunk's output-gate rows right after storing the previous chunk's outputs (temporaries that aliased the gate registers renamed)
# baseline (speedup 1.0000x reference)
.LBB0_989:
	s_waitcnt vmcnt(0)
	v_permlane32_swap_b32_e32 v190, v192
	v_permlane32_swap_b32_e32 v191, v193
	v_permlane32_swap_b32_e32 v184, v186
	v_permlane32_swap_b32_e32 v185, v187
	s_nop 1
	s_add_i32 s63, s64, 0xffffff80
	s_and_b32 s63, s63, 0x80
	v_lshl_add_u32 v20, s63, 2, v135
	ds_read2_b32 v[18:19], v20 offset1:32
	ds_read2_b32 v[20:21], v20 offset0:64 offset1:96
	s_mul_i32 s62, s66, 0xab
	s_bfe_u32 s62, s62, 0x70009
	s_mul_i32 s62, s62, 3
	s_waitcnt lgkmcnt(1)
	v_mov_b32_e32 v22, v18
	s_waitcnt lgkmcnt(0)
	v_mov_b32_e32 v23, v20
	v_mov_b32_e32 v20, v19
	v_pk_add_f32 v[18:19], v[22:23], v[20:21]
	s_sub_i32 s62, s66, s62
	v_add_f32_e32 v18, v18, v19
	v_fmamk_f32 v18, v18, 0x3c000000, v208
	v_mul_f32_e32 v19, 0x4b800000, v18
	v_cmp_gt_f32_e32 vcc, s71, v18
	v_ashrrev_i32_e32 v199, 31, v198
	s_and_b32 s62, s62, 0xff
	v_cndmask_b32_e32 v18, v18, v19, vcc
	v_rsq_f32_e32 v18, v18
	s_mul_i32 s62, s62, 0x8400
	s_add_i32 s62, s62, 0
	v_lshl_add_u32 v212, v137, 4, s62
	v_mul_f32_e32 v19, 0x45800000, v18
	v_cndmask_b32_e32 v50, v18, v19, vcc
	v_lshlrev_b64 v[18:19], 12, v[198:199]
	v_pk_mul_f32 v[2:3], v[2:3], v[50:51] op_sel_hi:[1,0]
	v_lshl_add_u64 v[200:201], v[188:189], 0, v[18:19]
	s_waitcnt vmcnt(7)
	v_pk_mul_f32 v[2:3], v[94:95], v[2:3]
	s_waitcnt vmcnt(3)
	v_lshlrev_b32_e32 v18, 16, v192
	v_and_b32_e32 v19, 0xffff0000, v192
	v_pk_mul_f32 v[2:3], v[2:3], v[18:19]
	ds_read_b128 v[214:217], v212
	v_cvt_pk_bf16_f32 v192, v2, v3
	v_pk_mul_f32 v[2:3], v[4:5], v[50:51] op_sel_hi:[1,0]
	v_lshlrev_b32_e32 v22, 16, v193
	v_pk_mul_f32 v[20:21], v[96:97], v[2:3]
	ds_read_b128 v[2:5], v212 offset:8192
	v_and_b32_e32 v23, 0xffff0000, v193
	v_pk_mul_f32 v[20:21], v[20:21], v[22:23]
	v_pk_mul_f32 v[12:13], v[12:13], v[50:51] op_sel_hi:[1,0]
	v_cvt_pk_bf16_f32 v193, v20, v21
	s_waitcnt lgkmcnt(0)
	v_mfma_f32_32x32x16_bf16 v[18:33], v[2:5], v[214:217], 0
	ds_read_b128 v[34:37], v212 offset:9216
	ds_read_b128 v[218:221], v212 offset:1024
	v_mul_f32_e64 v2, v6, v50
	v_mul_f32_e64 v3, v7, v50
	s_waitcnt vmcnt(3)
	v_lshlrev_b32_e32 v4, 16, v190
	v_pk_mul_f32 v[2:3], v[90:91], v[2:3]
	v_and_b32_e32 v5, 0xffff0000, v190
	v_pk_mul_f32 v[2:3], v[2:3], v[4:5]
	ds_read_b128 v[222:225], v212 offset:2048
	v_cvt_pk_bf16_f32 v190, v2, v3
	ds_read_b128 v[2:5], v212 offset:10240
	s_waitcnt lgkmcnt(2)
	v_mfma_f32_32x32x16_bf16 v[18:33], v[34:37], v[218:221], v[18:33]
	v_mul_f32_e64 v6, v8, v50
	v_mul_f32_e64 v7, v9, v50
	v_lshlrev_b32_e32 v36, 16, v191
	v_mul_f32_e64 v34, v92, v6
	v_mul_f32_e64 v35, v93, v7
	ds_read_b128 v[6:9], v212 offset:11264
	ds_read_b128 v[238:241], v212 offset:3072
	v_and_b32_e32 v37, 0xffff0000, v191
	ds_read_b128 v[46:49], v212 offset:4096
	v_add_u32_e32 v199, s62, v139
	s_waitcnt lgkmcnt(3)
	v_mfma_f32_32x32x16_bf16 v[18:33], v[2:5], v[222:225], v[18:33]
	v_mul_f32_e64 v2, v34, v36
	v_mul_f32_e64 v3, v35, v37
	s_waitcnt vmcnt(2)
	v_lshlrev_b32_e32 v34, 16, v186
	v_cvt_pk_bf16_f32 v191, v2, v3
	v_pk_mul_f32 v[2:3], v[10:11], v[50:51] op_sel_hi:[1,0]
	v_and_b32_e32 v35, 0xffff0000, v186
	v_pk_mul_f32 v[10:11], v[86:87], v[2:3]
	ds_read_b128 v[2:5], v212 offset:12288
	s_waitcnt lgkmcnt(2)
	v_mfma_f32_32x32x16_bf16 v[18:33], v[6:9], v[238:241], v[18:33]
	v_mul_f32_e64 v6, v10, v34
	v_mul_f32_e64 v7, v11, v35
	v_add_u32_e32 v198, 32, v198
	v_cvt_pk_bf16_f32 v186, v6, v7
	ds_read_b128 v[6:9], v212 offset:13312
	ds_read_b128 v[42:45], v212 offset:5120
	ds_read_b128 v[38:41], v212 offset:6144
	s_waitcnt lgkmcnt(3)
	v_mfma_f32_32x32x16_bf16 v[18:33], v[2:5], v[46:49], v[18:33]
	v_mul_f32_e64 v2, v88, v12
	v_mul_f32_e64 v3, v89, v13
	v_lshlrev_b32_e32 v4, 16, v187
	v_and_b32_e32 v5, 0xffff0000, v187
	v_mul_f32_e64 v2, v2, v4
	v_mul_f32_e64 v3, v3, v5
	s_waitcnt vmcnt(2)
	v_lshlrev_b32_e32 v12, 16, v184
	v_cvt_pk_bf16_f32 v187, v2, v3
	ds_read_b128 v[2:5], v212 offset:14336
	s_waitcnt lgkmcnt(2)
	v_mfma_f32_32x32x16_bf16 v[18:33], v[6:9], v[42:45], v[18:33]
	v_mul_f32_e64 v6, v14, v50
	v_mul_f32_e64 v7, v15, v50
	v_and_b32_e32 v13, 0xffff0000, v184
	v_mul_f32_e64 v10, v82, v6
	v_mul_f32_e64 v11, v83, v7
	ds_read_b128 v[6:9], v212 offset:15360
	ds_read_b128 v[34:37], v212 offset:7168
	s_waitcnt lgkmcnt(2)
	v_mfma_f32_32x32x16_bf16 v[18:33], v[2:5], v[38:41], v[18:33]
	v_mul_f32_e64 v2, v10, v12
	v_mul_f32_e64 v3, v11, v13
	v_add_u32_e32 v10, s68, v212
	ds_read_b128 v[54:57], v10 offset:24576
	v_cvt_pk_bf16_f32 v184, v2, v3
	v_pk_mul_f32 v[2:3], v[16:17], v[50:51] op_sel_hi:[1,0]
	v_lshlrev_b32_e32 v4, 16, v185
	v_pk_mul_f32 v[2:3], v[84:85], v[2:3]
	s_waitcnt lgkmcnt(1)
	v_mfma_f32_32x32x16_bf16 v[18:33], v[6:9], v[34:37], v[18:33]
	v_and_b32_e32 v5, 0xffff0000, v185
	v_mul_f32_e64 v165, v2, v4
	v_mul_f32_e64 v167, v3, v5
	ds_read_b128 v[50:53], v10 offset:28672
	v_cvt_pk_bf16_f32 v185, v165, v167
	s_nop 1
	v_permlane32_swap_b32_e32 v190, v192
	v_permlane32_swap_b32_e32 v191, v193
	v_permlane32_swap_b32_e32 v184, v186
	v_permlane32_swap_b32_e32 v185, v187
	global_store_dwordx4 v[200:201], v[190:193], off
	global_store_dwordx4 v[200:201], v[184:187], off offset:32
	s_nop 1
	v_mad_i64_i32 v[184:185], s[100:101], v198, s70, v[182:183]
	global_load_dwordx4 v[190:193], v[184:185], off
	global_load_dwordx4 v[184:187], v[184:185], off offset:32
	s_nop 6
	v_cndmask_b32_e64 v2, v18, 0, s[6:7]
	v_cndmask_b32_e64 v3, 0, v19, s[8:9]
	v_cndmask_b32_e64 v4, v20, 0, s[10:11]
	v_cndmask_b32_e64 v5, v21, 0, s[12:13]
	v_cndmask_b32_e64 v6, v22, 0, s[14:15]
	v_cndmask_b32_e64 v7, v23, 0, s[16:17]
	v_cndmask_b32_e64 v8, v24, 0, s[18:19]
	v_cndmask_b32_e64 v9, v25, 0, s[20:21]
	v_cvt_pk_bf16_f32 v2, v2, v3
	v_cvt_pk_bf16_f32 v3, v4, v5
	v_cvt_pk_bf16_f32 v4, v6, v7
	v_cvt_pk_bf16_f32 v5, v8, v9
	v_cndmask_b32_e64 v18, v26, 0, s[22:23]
	v_cndmask_b32_e64 v19, v27, 0, s[24:25]
	s_waitcnt lgkmcnt(1)
	v_mfma_f32_32x32x16_bf16 v[2:17], v[54:57], v[2:5], 0
	v_cndmask_b32_e64 v20, v28, 0, s[26:27]
	v_cndmask_b32_e64 v21, v29, 0, s[28:29]
	v_cndmask_b32_e64 v26, v30, 0, s[30:31]
	v_cndmask_b32_e64 v27, v31, 0, s[34:35]
	v_cvt_pk_bf16_f32 v18, v18, v19
	v_cvt_pk_bf16_f32 v19, v20, v21
	ds_read_b128 v[22:25], v199 offset:33280
	v_cvt_pk_bf16_f32 v20, v26, v27
	ds_read_b128 v[26:29], v199 offset:33312
	v_cndmask_b32_e64 v30, v32, 0, s[36:37]
	v_cndmask_b32_e64 v31, v33, 0, s[38:39]
	v_cvt_pk_bf16_f32 v21, v30, v31
	s_waitcnt lgkmcnt(1)
	v_pk_mul_f32 v[30:31], v[102:103], v[22:23]
	v_pk_mul_f32 v[32:33], v[104:105], v[24:25]
	v_mfma_f32_32x32x16_bf16 v[2:17], v[50:53], v[18:21], v[2:17]
	s_waitcnt lgkmcnt(0)
	v_mul_f32_e64 v165, v106, v26
	v_mul_f32_e64 v167, v107, v27
	v_mul_f32_e64 v169, v108, v28
	v_mul_f32_e64 v180, v109, v29
	v_cvt_pk_bf16_f32 v26, v30, v31
	v_cvt_pk_bf16_f32 v27, v32, v33
	v_cvt_pk_bf16_f32 v28, v165, v167
	v_cvt_pk_bf16_f32 v29, v169, v180
	ds_read_b128 v[18:21], v199 offset:33344
	ds_read_b128 v[22:25], v199 offset:33376
	v_mfma_f32_32x32x16_bf16 v[2:17], v[26:29], v[214:217], v[2:17]
	s_waitcnt lgkmcnt(1)
	v_mul_f32_e64 v18, v110, v18
	v_mul_f32_e64 v19, v111, v19
	v_mul_f32_e64 v20, v112, v20
	v_mul_f32_e64 v21, v113, v21
	s_waitcnt lgkmcnt(0)
	v_pk_mul_f32 v[22:23], v[114:115], v[22:23]
	v_cvt_pk_bf16_f32 v18, v18, v19
	v_cvt_pk_bf16_f32 v19, v20, v21
	v_cvt_pk_bf16_f32 v20, v22, v23
	v_pk_mul_f32 v[22:23], v[116:117], v[24:25]
	ds_read_b128 v[26:29], v199 offset:33440
	v_cvt_pk_bf16_f32 v21, v22, v23
	ds_read_b128 v[22:25], v199 offset:33408
	v_mfma_f32_32x32x16_bf16 v[2:17], v[18:21], v[218:221], v[2:17]
	s_waitcnt lgkmcnt(0)
	v_mul_f32_e64 v30, v118, v22
	v_mul_f32_e64 v31, v119, v23
	v_mul_f32_e64 v32, v120, v24
	v_mul_f32_e64 v33, v121, v25
	ds_read_b128 v[18:21], v199 offset:33472
	ds_read_b128 v[22:25], v199 offset:33504
	v_mul_f32_e64 v165, v122, v26
	v_mul_f32_e64 v167, v123, v27
	v_mul_f32_e64 v169, v124, v28
	v_mul_f32_e64 v180, v125, v29
	v_cvt_pk_bf16_f32 v26, v30, v31
	v_cvt_pk_bf16_f32 v27, v32, v33
	v_cvt_pk_bf16_f32 v28, v165, v167
	v_cvt_pk_bf16_f32 v29, v169, v180
	s_waitcnt lgkmcnt(1)
	v_pk_mul_f32 v[18:19], v[126:127], v[18:19]
	v_pk_mul_f32 v[20:21], v[128:129], v[20:21]
	s_waitcnt lgkmcnt(0)
	v_pk_mul_f32 v[22:23], v[130:131], v[22:23]
	v_cvt_pk_bf16_f32 v18, v18, v19
	v_cvt_pk_bf16_f32 v19, v20, v21
	v_cvt_pk_bf16_f32 v20, v22, v23
	v_pk_mul_f32 v[22:23], v[132:133], v[24:25]
	v_mfma_f32_32x32x16_bf16 v[2:17], v[26:29], v[222:225], v[2:17]
	v_cvt_pk_bf16_f32 v21, v22, v23
	ds_read_b128 v[22:25], v199 offset:33536
	ds_read_b128 v[26:29], v199 offset:33568
	s_waitcnt lgkmcnt(1)
	v_pk_mul_f32 v[30:31], v[196:197], v[22:23]
	v_pk_mul_f32 v[32:33], v[194:195], v[24:25]
	v_mfma_f32_32x32x16_bf16 v[2:17], v[18:21], v[238:241], v[2:17]
	s_waitcnt lgkmcnt(0)
	v_mul_f32_e64 v200, v100, v26
	v_mul_f32_e64 v201, v101, v27
	v_mul_f32_e64 v214, v98, v28
	v_mul_f32_e64 v215, v99, v29
	v_cvt_pk_bf16_f32 v26, v30, v31
	v_cvt_pk_bf16_f32 v27, v32, v33
	v_cvt_pk_bf16_f32 v28, v200, v201
	v_cvt_pk_bf16_f32 v29, v214, v215
	ds_read_b128 v[18:21], v199 offset:33600
	ds_read_b128 v[22:25], v199 offset:33632
	v_mfma_f32_32x32x16_bf16 v[2:17], v[26:29], v[46:49], v[2:17]
	s_waitcnt lgkmcnt(1)
	v_mul_f32_e64 v18, v58, v18
	v_mul_f32_e64 v19, v59, v19
	v_mul_f32_e64 v20, v60, v20
	v_mul_f32_e64 v21, v61, v21
	s_waitcnt lgkmcnt(0)
	v_pk_mul_f32 v[22:23], v[62:63], v[22:23]
	v_cvt_pk_bf16_f32 v18, v18, v19
	v_cvt_pk_bf16_f32 v19, v20, v21
	v_cvt_pk_bf16_f32 v20, v22, v23
	v_pk_mul_f32 v[22:23], v[64:65], v[24:25]
	s_nop 0
	v_cvt_pk_bf16_f32 v21, v22, v23
	ds_read_b128 v[22:25], v199 offset:33664
	ds_read_b128 v[26:29], v199 offset:33696
	v_mfma_f32_32x32x16_bf16 v[2:17], v[18:21], v[42:45], v[2:17]
	s_waitcnt lgkmcnt(1)
	v_mul_f32_e64 v30, v66, v22
	v_mul_f32_e64 v31, v67, v23
	v_mul_f32_e64 v32, v68, v24
	v_mul_f32_e64 v33, v69, v25
	s_waitcnt lgkmcnt(0)
	v_pk_mul_f32 v[42:43], v[70:71], v[26:27]
	v_pk_mul_f32 v[44:45], v[72:73], v[28:29]
	v_cvt_pk_bf16_f32 v26, v30, v31
	v_cvt_pk_bf16_f32 v27, v32, v33
	v_cvt_pk_bf16_f32 v28, v42, v43
	v_cvt_pk_bf16_f32 v29, v44, v45
	ds_read_b128 v[18:21], v199 offset:33728
	ds_read_b128 v[22:25], v199 offset:33760
	v_mfma_f32_32x32x16_bf16 v[2:17], v[26:29], v[38:41], v[2:17]
	s_waitcnt lgkmcnt(1)
	v_mul_f32_e64 v18, v74, v18
	v_mul_f32_e64 v19, v75, v19
	v_mul_f32_e64 v20, v76, v20
	v_mul_f32_e64 v21, v77, v21
	s_waitcnt lgkmcnt(0)
	v_pk_mul_f32 v[22:23], v[78:79], v[22:23]
	v_cvt_pk_bf16_f32 v18, v18, v19
	v_cvt_pk_bf16_f32 v19, v20, v21
	v_cvt_pk_bf16_f32 v20, v22, v23
	v_pk_mul_f32 v[22:23], v[80:81], v[24:25]
	s_nop 0
	v_cvt_pk_bf16_f32 v21, v22, v23
	s_nop 1
	v_mfma_f32_32x32x16_bf16 v[2:17], v[18:21], v[34:37], v[2:17]
	s_nop 11
	v_mul_f32_e32 v18, v3, v3
	v_fmac_f32_e32 v18, v2, v2
	v_fmac_f32_e32 v18, v4, v4
	v_fmac_f32_e32 v18, v5, v5
	v_fmac_f32_e32 v18, v6, v6
	v_fmac_f32_e32 v18, v7, v7
	v_fmac_f32_e32 v18, v8, v8
	v_fmac_f32_e32 v18, v9, v9
	v_fmac_f32_e32 v18, v10, v10
	v_fmac_f32_e32 v18, v11, v11
	v_fmac_f32_e32 v18, v12, v12
	v_fmac_f32_e32 v18, v13, v13
	v_fmac_f32_e32 v18, v14, v14
	v_fmac_f32_e32 v18, v15, v15
	v_fmac_f32_e32 v18, v16, v16
	v_fmac_f32_e32 v18, v17, v17
	ds_bpermute_b32 v19, v210, v18
	s_and_saveexec_b64 s[62:63], s[4:5]
	s_cbranch_execz .LBB0_988
	s_and_b32 s65, s64, 0x80
	s_waitcnt lgkmcnt(0)
	v_add_f32_e32 v18, v18, v19
	v_lshl_add_u32 v19, s65, 2, v211
	ds_write_b32 v19, v18
	s_branch .LBB0_988
